# P6: half of the workgroups (bit 3 of blockIdx) start the gate-up GEMM 2.5 us later so the per-tile store bursts of the two halves interleave
# speedup vs baseline: 1.0016x; 1.0016x over previous
.LBB0_675:
	s_cmp_lt_i32 s30, 7
	s_cselect_b64 s[2:3], -1, 0
	s_and_b64 s[2:3], s[2:3], s[0:1]
	s_andn2_b64 vcc, exec, s[2:3]
	s_cbranch_vccnz .LBB0_694
	s_cmpk_gt_i32 s70, 0xaff
	v_readfirstlane_b32 s1, v189
	s_cbranch_scc1 .LBB0_694
	s_lshr_b32 s98, s70, 3
	s_and_b32 s98, s98, 1
	s_cmp_eq_u32 s98, 0
	s_cbranch_scc1 .Lstag6_done
	s_mul_i32 s101, s98, 250
	s_memrealtime s[98:99]
	s_waitcnt lgkmcnt(0)
	s_add_u32 s101, s98, s101
.Lstag6_wait:
	s_sleep 8
	s_memrealtime s[98:99]
	s_waitcnt lgkmcnt(0)
	s_sub_u32 s98, s98, s101
	s_cmp_lt_i32 s98, 0
	s_cbranch_scc1 .Lstag6_wait
.Lstag6_done:
	s_waitcnt vmcnt(0)
	v_lshrrev_b32_e32 v2, 1, v189
	v_and_b32_e32 v11, 24, v2
	v_lshrrev_b32_e32 v2, 5, v189
	v_and_b32_e32 v2, 4, v2
	s_waitcnt lgkmcnt(0)
	v_bfe_u32 v3, v189, 2, 2
	v_lshlrev_b32_e32 v0, 4, v189
	v_and_b32_e32 v1, 32, v189
	v_bfe_u32 v10, v189, 2, 4
	v_or3_b32 v2, v2, v3, v11
	v_lshrrev_b32_e32 v3, 3, v189
	s_movk_i32 s0, 0x70
	v_bitop3_b32 v8, v0, v1, 48 bitop3:0x6c
	v_and_b32_e32 v9, 64, v189
	v_and_or_b32 v4, v3, s0, v10
	s_movk_i32 s0, 0x60
	v_add_u32_e32 v12, 0x2000, v0
	v_or_b32_e32 v1, v8, v9
	v_and_or_b32 v3, v3, s0, v2
	v_lshrrev_b32_e32 v0, 7, v12
	s_movk_i32 s0, 0xf0
	v_lshl_or_b32 v130, v3, 11, v1
	v_and_or_b32 v3, v0, s0, v10
	s_movk_i32 s0, 0xe0
	s_ashr_i32 s45, s70, 31
	v_and_or_b32 v0, v0, s0, v2
	s_lshr_b32 s0, s45, 29
	s_add_i32 s0, s70, s0
	s_lshr_b32 s11, s1, 8
	s_lshr_b32 s10, s1, 6
	s_ashr_i32 s6, s0, 3
	s_and_b32 s0, s0, -8
	s_lshl_b32 s44, s10, 10
	s_lshl_b32 s12, s11, 6
	s_sub_i32 s0, s70, s0
	s_cmp_lt_i32 s0, 0
	s_movk_i32 s46, 0x161
	s_cselect_b32 s7, s46, 0x160
	s_mul_i32 s0, s0, s7
	s_add_i32 s0, s0, s6
	s_mul_hi_i32 s6, s0, 0x2e8ba2e9
	s_lshr_b32 s7, s6, 31
	s_ashr_i32 s6, s6, 5
	s_add_i32 s6, s6, s7
	s_lshl_b32 s7, s6, 3
	s_mulk_i32 s6, 0xb0
	s_sub_i32 s6, s0, s6
	s_sext_i32_i16 s0, s6
	s_bfe_u32 s0, s0, 0x3001c
	s_add_i32 s13, s6, s0
	s_sext_i32_i16 s0, s13
	s_and_b32 s13, s13, 0xfff8
	s_sub_i32 s6, s6, s13
	s_sext_i32_i16 s6, s6
	s_lshr_b32 s0, s0, 3
	s_add_i32 s36, s7, s6
	s_ashr_i32 s37, s36, 31
	s_bfe_i64 s[14:15], s[0:1], 0x100000
	s_lshl_b64 s[6:7], s[36:37], 19
	s_lshl_b64 s[14:15], s[14:15], 19
	s_add_u32 s38, s72, s14
	s_addc_u32 s39, s73, s15
	s_lshl_b32 s13, s36, 8
	v_and_b32_e32 v13, 15, v189
	s_add_i32 s13, s13, s12
	v_lshl_or_b32 v134, v0, 11, v1
	v_or_b32_e32 v0, s13, v13
	v_lshl_or_b32 v128, v4, 11, v1
	v_lshl_or_b32 v132, v3, 11, v1
	v_ashrrev_i32_e32 v1, 31, v0
	s_add_i32 s37, s44, 0
	v_lshl_add_u64 v[0:1], v[0:1], 2, s[8:9]
	s_add_i32 m0, s37, 0x10000
	global_load_dword v166, v[0:1], off
	global_load_dword v165, v[0:1], off offset:64
	global_load_dword v164, v[0:1], off offset:128
	global_load_dword v163, v[0:1], off offset:192
	global_load_dword v162, v[0:1], off offset:512
	global_load_dword v161, v[0:1], off offset:576
	global_load_dword v152, v[0:1], off offset:640
	global_load_dword v149, v[0:1], off offset:704
	v_mov_b32_e32 v131, 0
	global_load_lds_dwordx4 v130, s[38:39]
	s_add_i32 m0, s37, 0x12000
	s_add_u32 s14, s38, 0x40000
	global_load_lds_dwordx4 v134, s[38:39]
	s_addc_u32 s15, s39, 0
	s_add_i32 m0, s37, 0x14000
	v_mov_b32_e32 v135, v131
	global_load_lds_dwordx4 v130, s[14:15]
	s_add_i32 m0, s37, 0x16000
	s_add_u32 s40, s4, s6
	s_addc_u32 s41, s5, s7
	s_add_i32 s47, s37, 0x2000
	global_load_lds_dwordx4 v134, s[14:15]
	s_mov_b32 m0, s37
	s_add_u32 s6, s40, 0x40000
	global_load_lds_dwordx4 v128, s[40:41]
	s_mov_b32 m0, s47
	s_addc_u32 s7, s41, 0
	s_add_i32 s48, s37, 0x4000
	global_load_lds_dwordx4 v132, s[40:41]
	s_mov_b32 m0, s48
	s_add_i32 s49, s37, 0x6000
	global_load_lds_dwordx4 v128, s[6:7]
	s_mov_b32 m0, s49
	v_mov_b32_e32 v129, v131
	global_load_lds_dwordx4 v132, s[6:7]
	v_mov_b32_e32 v133, v131
	s_cmp_eq_u32 s11, 1
	s_mov_b32 s50, 0
	v_lshl_add_u64 v[6:7], s[38:39], 0, v[130:131]
	v_lshl_add_u64 v[4:5], s[38:39], 0, v[134:135]
	v_lshl_add_u64 v[0:1], s[40:41], 0, v[128:129]
	s_cselect_b64 s[6:7], -1, 0
	s_cmp_lg_u32 s11, 1
	v_lshl_add_u64 v[2:3], s[40:41], 0, v[132:133]
	s_cbranch_scc1 .LBB0_679
	s_barrier
